# p3a S1: silu pairs use one packed multiply (-log2e*y) and one packed add (1+e) instead of two scalar ops each (64 fewer VALU instructions per k-head iteration)
# speedup vs baseline: 1.0032x; 1.0032x over previous
.LBB0_500:
	v_mov_b32_e32 v246, 0xbfb8aa3b
	v_lshlrev_b32_e32 v20, 16, v114
	v_and_b32_e32 v21, 0xffff0000, v114
	v_lshlrev_b32_e32 v34, 16, v118
	v_and_b32_e32 v35, 0xffff0000, v118
	s_waitcnt vmcnt(6)
	v_pk_fma_f32 v[20:21], v[6:7], v[20:21], 0 op_sel_hi:[1,1,0]
	v_lshlrev_b32_e32 v42, 16, v122
	v_and_b32_e32 v43, 0xffff0000, v122
	s_waitcnt vmcnt(5)
	v_pk_fma_f32 v[20:21], v[10:11], v[34:35], v[20:21]
	v_lshlrev_b32_e32 v50, 16, v126
	v_and_b32_e32 v51, 0xffff0000, v126
	s_waitcnt vmcnt(3)
	v_pk_fma_f32 v[20:21], v[98:99], v[42:43], v[20:21]
	v_lshlrev_b32_e32 v32, 16, v119
	s_waitcnt vmcnt(1)
	v_pk_fma_f32 v[20:21], v[106:107], v[50:51], v[20:21]
	v_and_b32_e32 v33, 0xffff0000, v119
	v_pk_mul_f32 v[226:227], v[20:21], v[246:247] op_sel_hi:[1,0]
	v_exp_f32_e32 v226, v226
	v_exp_f32_e32 v227, v227
	v_lshlrev_b32_e32 v40, 16, v123
	v_and_b32_e32 v41, 0xffff0000, v123
	v_pk_add_f32 v[226:227], v[226:227], 1.0 op_sel_hi:[1,0]
	v_rcp_f32_e32 v226, v226
	v_rcp_f32_e32 v227, v227
	v_lshlrev_b32_e32 v46, 16, v127
	v_and_b32_e32 v47, 0xffff0000, v127
	v_lshlrev_b32_e32 v52, 16, v116
	v_pk_mul_f32 v[20:21], v[20:21], v[226:227]
	v_lshlrev_b32_e32 v22, 16, v115
	v_and_b32_e32 v23, 0xffff0000, v115
	v_pk_fma_f32 v[22:23], v[8:9], v[22:23], 0 op_sel_hi:[1,1,0]
	v_and_b32_e32 v53, 0xffff0000, v116
	v_pk_fma_f32 v[22:23], v[12:13], v[32:33], v[22:23]
	v_lshlrev_b32_e32 v30, 16, v120
	v_pk_fma_f32 v[22:23], v[100:101], v[40:41], v[22:23]
	v_and_b32_e32 v31, 0xffff0000, v120
	v_pk_fma_f32 v[22:23], v[108:109], v[46:47], v[22:23]
	v_pk_fma_f32 v[52:53], v[2:3], v[52:53], 0 op_sel_hi:[1,1,0]
	v_pk_mul_f32 v[226:227], v[22:23], v[246:247] op_sel_hi:[1,0]
	v_exp_f32_e32 v226, v226
	v_exp_f32_e32 v227, v227
	v_lshlrev_b32_e32 v38, 16, v124
	v_and_b32_e32 v39, 0xffff0000, v124
	v_pk_fma_f32 v[52:53], v[14:15], v[30:31], v[52:53]
	v_lshlrev_b32_e32 v48, 16, v128
	v_and_b32_e32 v49, 0xffff0000, v128
	v_pk_fma_f32 v[52:53], v[102:103], v[38:39], v[52:53]
	s_waitcnt vmcnt(0)
	s_cmp_eq_u32 s64, 0
	s_cbranch_scc0 .Lp3a_s2h_skip
	s_or_b32 s98, s64, s84
	s_lshl_b32 s98, s98, 1
	v_readlane_b32 s99, v249, 49
	v_readlane_b32 s100, v249, 47
	v_readlane_b32 s101, v249, 48
	v_mov_b32_e32 v244, v1
	v_mov_b32_e32 v245, 0
	s_or_b32 s98, s98, s99
	s_lshl_b32 s98, s98, 2
	v_lshl_add_u64 v[244:245], s[88:89], 0, v[244:245]
	s_add_u32 s100, s100, s98
	s_addc_u32 s101, s101, 0
	v_lshlrev_b64 v[244:245], 8, v[244:245]
	s_nop 1
	v_lshl_add_u64 v[244:245], s[100:101], 0, v[244:245]
	s_add_u32 s100, s60, s98
	s_addc_u32 s101, s61, 0
	global_load_dword v240, v[244:245], off
	global_load_dword v241, v[244:245], off offset:128
	global_load_dword v242, v18, s[100:101]
	s_add_u32 s100, s58, s98
	s_addc_u32 s101, s59, 0
	global_load_dword v243, v18, s[100:101]
.Lp3a_s2h_skip:
	v_pk_fma_f32 v[52:53], v[110:111], v[48:49], v[52:53]
	v_pk_add_f32 v[226:227], v[226:227], 1.0 op_sel_hi:[1,0]
	v_pk_mul_f32 v[228:229], v[52:53], v[246:247] op_sel_hi:[1,0]
	v_rcp_f32_e32 v226, v226
	v_rcp_f32_e32 v227, v227
	v_exp_f32_e32 v228, v228
	v_exp_f32_e32 v229, v229
	v_lshlrev_b32_e32 v28, 16, v121
	v_pk_mul_f32 v[22:23], v[22:23], v[226:227]
	v_pk_add_f32 v[228:229], v[228:229], 1.0 op_sel_hi:[1,0]
	v_lshlrev_b32_e32 v54, 16, v117
	v_and_b32_e32 v55, 0xffff0000, v117
	v_and_b32_e32 v29, 0xffff0000, v121
	v_pk_fma_f32 v[54:55], v[4:5], v[54:55], 0 op_sel_hi:[1,1,0]
	v_lshlrev_b32_e32 v36, 16, v125
	v_and_b32_e32 v37, 0xffff0000, v125
	v_pk_fma_f32 v[54:55], v[16:17], v[28:29], v[54:55]
	v_lshlrev_b32_e32 v44, 16, v129
	v_and_b32_e32 v45, 0xffff0000, v129
	v_pk_fma_f32 v[54:55], v[104:105], v[36:37], v[54:55]
	v_rcp_f32_e32 v228, v228
	v_pk_fma_f32 v[54:55], v[112:113], v[44:45], v[54:55]
	v_rcp_f32_e32 v229, v229
	v_pk_mul_f32 v[226:227], v[54:55], v[246:247] op_sel_hi:[1,0]
	v_exp_f32_e32 v226, v226
	v_exp_f32_e32 v227, v227
	v_pk_mul_f32 v[24:25], v[20:21], v[20:21]
	v_pk_mul_f32 v[58:59], v[22:23], v[22:23]
	v_pk_add_f32 v[226:227], v[226:227], 1.0 op_sel_hi:[1,0]
	v_rcp_f32_e32 v226, v226
	v_rcp_f32_e32 v227, v227
	v_add_f32_e32 v24, v24, v25
	v_pk_mul_f32 v[52:53], v[52:53], v[228:229]
	v_add_f32_e32 v24, v58, v24
	v_and_b32_e32 v167, 64, v184
	v_pk_mul_f32 v[26:27], v[52:53], v[52:53]
	v_add_f32_e32 v24, v59, v24
	v_xor_b32_e32 v19, 1, v184
	v_add_u32_e32 v60, 64, v167
	v_pk_mul_f32 v[54:55], v[54:55], v[226:227]
	v_add_f32_e32 v24, v26, v24
	v_cmp_lt_i32_e32 vcc, v19, v60
	v_pk_mul_f32 v[56:57], v[54:55], v[54:55]
	v_add_f32_e32 v24, v27, v24
	v_cndmask_b32_e32 v19, v184, v19, vcc
	v_add_f32_e32 v24, v56, v24
	v_lshlrev_b32_e32 v19, 2, v19
	v_add_f32_e32 v24, v57, v24
	v_xor_b32_e32 v26, 2, v184
	v_cmp_lt_i32_e32 vcc, v26, v60
	v_mov_b32_e32 v160, v1
	s_nop 1
	v_add_f32_dpp v24, v24, v24 quad_perm:[1,0,3,2] row_mask:0xf bank_mask:0xf
	v_cndmask_b32_e32 v26, v184, v26, vcc
	v_lshlrev_b32_e32 v168, 2, v26
	v_xor_b32_e32 v26, 4, v184
	v_cmp_lt_i32_e32 vcc, v26, v60
	v_cmp_gt_i32_e64 s[6:7], 16, v160
	v_mov_b32_e32 v56, 1.0
	v_cndmask_b32_e32 v26, v184, v26, vcc
	v_lshlrev_b32_e32 v173, 2, v26
	s_nop 1
	v_add_f32_dpp v24, v24, v24 quad_perm:[2,3,0,1] row_mask:0xf bank_mask:0xf
	v_xor_b32_e32 v26, 8, v184
	v_cmp_lt_i32_e32 vcc, v26, v60
	v_cndmask_b32_e64 v161, 1.0, v187, s[6:7]
	v_cmp_gt_i32_e64 s[4:5], 32, v160
	v_cndmask_b32_e32 v26, v184, v26, vcc
	v_lshlrev_b32_e32 v175, 2, v26
	s_nop 1
	v_add_f32_dpp v24, v24, v24 row_half_mirror row_mask:0xf bank_mask:0xf
	s_nop 1
	v_add_f32_dpp v24, v24, v24 row_mirror row_mask:0xf bank_mask:0xf
	s_and_saveexec_b64 s[8:9], s[4:5]
	s_cbranch_execz .LBB0_502
	v_add_f32_e32 v24, 0x358637bd, v24
	v_mul_f32_e32 v25, 0x4b800000, v24
	v_cmp_gt_f32_e32 vcc, s48, v24
	s_nop 1
	v_cndmask_b32_e32 v24, v24, v25, vcc
	v_rsq_f32_e32 v24, v24
	s_nop 0
	v_mul_f32_e32 v25, 0x45800000, v24
	v_cndmask_b32_e32 v24, v24, v25, vcc
	v_mul_f32_e32 v56, v161, v24

.LBB0_504:
	s_or_b64 exec, exec, s[8:9]
	v_pk_fma_f32 v[34:35], v[6:7], v[34:35], 0 op_sel_hi:[1,1,0]
	v_lshlrev_b32_e32 v60, 16, v130
	v_pk_fma_f32 v[34:35], v[10:11], v[42:43], v[34:35]
	v_and_b32_e32 v61, 0xffff0000, v130
	v_pk_fma_f32 v[34:35], v[98:99], v[50:51], v[34:35]
	v_pk_fma_f32 v[32:33], v[8:9], v[32:33], 0 op_sel_hi:[1,1,0]
	v_pk_fma_f32 v[34:35], v[106:107], v[60:61], v[34:35]
	v_pk_fma_f32 v[32:33], v[12:13], v[40:41], v[32:33]
	v_pk_mul_f32 v[226:227], v[34:35], v[246:247] op_sel_hi:[1,0]
	v_exp_f32_e32 v226, v226
	v_exp_f32_e32 v227, v227
	v_lshlrev_b32_e32 v58, 16, v131
	v_and_b32_e32 v59, 0xffff0000, v131
	v_pk_add_f32 v[226:227], v[226:227], 1.0 op_sel_hi:[1,0]
	v_rcp_f32_e32 v226, v226
	v_rcp_f32_e32 v227, v227
	v_pk_fma_f32 v[32:33], v[100:101], v[46:47], v[32:33]
	v_pk_fma_f32 v[30:31], v[2:3], v[30:31], 0 op_sel_hi:[1,1,0]
	v_pk_fma_f32 v[32:33], v[108:109], v[58:59], v[32:33]
	v_pk_mul_f32 v[34:35], v[34:35], v[226:227]
	v_pk_mul_f32 v[226:227], v[32:33], v[246:247] op_sel_hi:[1,0]
	v_exp_f32_e32 v226, v226
	v_exp_f32_e32 v227, v227
	v_pk_fma_f32 v[30:31], v[14:15], v[38:39], v[30:31]
	v_lshlrev_b32_e32 v62, 16, v132
	v_pk_add_f32 v[226:227], v[226:227], 1.0 op_sel_hi:[1,0]
	v_and_b32_e32 v63, 0xffff0000, v132
	v_rcp_f32_e32 v226, v226
	v_rcp_f32_e32 v227, v227
	v_pk_fma_f32 v[30:31], v[102:103], v[48:49], v[30:31]
	v_pk_fma_f32 v[28:29], v[4:5], v[28:29], 0 op_sel_hi:[1,1,0]
	v_pk_fma_f32 v[64:65], v[110:111], v[62:63], v[30:31]
	v_pk_fma_f32 v[28:29], v[16:17], v[36:37], v[28:29]
	v_pk_mul_f32 v[228:229], v[64:65], v[246:247] op_sel_hi:[1,0]
	v_lshlrev_b32_e32 v56, 16, v133
	v_and_b32_e32 v57, 0xffff0000, v133
	v_exp_f32_e32 v228, v228
	v_pk_fma_f32 v[28:29], v[104:105], v[44:45], v[28:29]
	v_exp_f32_e32 v229, v229
	v_pk_mul_f32 v[30:31], v[32:33], v[226:227]
	v_pk_fma_f32 v[52:53], v[112:113], v[56:57], v[28:29]
	v_pk_mul_f32 v[226:227], v[52:53], v[246:247] op_sel_hi:[1,0]
	v_exp_f32_e32 v226, v226
	v_exp_f32_e32 v227, v227
	v_pk_add_f32 v[228:229], v[228:229], 1.0 op_sel_hi:[1,0]
	v_rcp_f32_e32 v228, v228
	v_rcp_f32_e32 v229, v229
	v_pk_add_f32 v[226:227], v[226:227], 1.0 op_sel_hi:[1,0]
	v_rcp_f32_e32 v226, v226
	v_pk_mul_f32 v[54:55], v[34:35], v[34:35]
	v_rcp_f32_e32 v227, v227
	v_pk_mul_f32 v[68:69], v[30:31], v[30:31]
	v_add_f32_e32 v54, v54, v55
	v_pk_mul_f32 v[28:29], v[64:65], v[228:229]
	v_add_f32_e32 v54, v68, v54
	v_pk_mul_f32 v[32:33], v[28:29], v[28:29]
	v_add_f32_e32 v54, v69, v54
	v_pk_mul_f32 v[52:53], v[52:53], v[226:227]
	v_add_f32_e32 v32, v32, v54
	v_pk_mul_f32 v[64:65], v[52:53], v[52:53]
	v_add_f32_e32 v32, v33, v32
	v_add_f32_e32 v32, v64, v32
	v_add_f32_e32 v32, v65, v32
	v_mov_b32_e32 v54, 1.0
	s_nop 1
	v_add_f32_dpp v32, v32, v32 quad_perm:[1,0,3,2] row_mask:0xf bank_mask:0xf
	s_nop 1
	v_add_f32_dpp v32, v32, v32 quad_perm:[2,3,0,1] row_mask:0xf bank_mask:0xf
	s_nop 1
	v_add_f32_dpp v32, v32, v32 row_half_mirror row_mask:0xf bank_mask:0xf
	s_nop 1
	v_add_f32_dpp v32, v32, v32 row_mirror row_mask:0xf bank_mask:0xf
	s_and_saveexec_b64 s[8:9], s[4:5]
	s_cbranch_execz .LBB0_506
	v_add_f32_e32 v32, 0x358637bd, v32
	v_mul_f32_e32 v33, 0x4b800000, v32
	v_cmp_gt_f32_e32 vcc, s48, v32
	s_nop 1
	v_cndmask_b32_e32 v32, v32, v33, vcc
	v_rsq_f32_e32 v32, v32
	s_nop 0
	v_mul_f32_e32 v33, 0x45800000, v32
	v_cndmask_b32_e32 v32, v32, v33, vcc
	v_mul_f32_e32 v54, v161, v32

.LBB0_508:
	s_or_b64 exec, exec, s[8:9]
	v_pk_fma_f32 v[42:43], v[6:7], v[42:43], 0 op_sel_hi:[1,1,0]
	v_lshlrev_b32_e32 v80, 16, v134
	v_pk_fma_f32 v[42:43], v[10:11], v[50:51], v[42:43]
	v_and_b32_e32 v81, 0xffff0000, v134
	v_pk_fma_f32 v[42:43], v[98:99], v[60:61], v[42:43]
	v_pk_fma_f32 v[40:41], v[8:9], v[40:41], 0 op_sel_hi:[1,1,0]
	v_pk_fma_f32 v[42:43], v[106:107], v[80:81], v[42:43]
	v_pk_fma_f32 v[40:41], v[12:13], v[46:47], v[40:41]
	v_pk_mul_f32 v[226:227], v[42:43], v[246:247] op_sel_hi:[1,0]
	v_exp_f32_e32 v226, v226
	v_exp_f32_e32 v227, v227
	v_lshlrev_b32_e32 v66, 16, v135
	v_and_b32_e32 v67, 0xffff0000, v135
	v_pk_add_f32 v[226:227], v[226:227], 1.0 op_sel_hi:[1,0]
	v_rcp_f32_e32 v226, v226
	v_rcp_f32_e32 v227, v227
	v_pk_fma_f32 v[40:41], v[100:101], v[58:59], v[40:41]
	v_pk_fma_f32 v[38:39], v[2:3], v[38:39], 0 op_sel_hi:[1,1,0]
	v_pk_fma_f32 v[40:41], v[108:109], v[66:67], v[40:41]
	v_pk_mul_f32 v[42:43], v[42:43], v[226:227]
	v_pk_mul_f32 v[226:227], v[40:41], v[246:247] op_sel_hi:[1,0]
	v_exp_f32_e32 v226, v226
	v_exp_f32_e32 v227, v227
	v_pk_fma_f32 v[38:39], v[14:15], v[48:49], v[38:39]
	v_lshlrev_b32_e32 v72, 16, v136
	v_pk_add_f32 v[226:227], v[226:227], 1.0 op_sel_hi:[1,0]
	v_and_b32_e32 v73, 0xffff0000, v136
	v_rcp_f32_e32 v226, v226
	v_rcp_f32_e32 v227, v227
	v_pk_fma_f32 v[38:39], v[102:103], v[62:63], v[38:39]
	v_pk_fma_f32 v[36:37], v[4:5], v[36:37], 0 op_sel_hi:[1,1,0]
	v_pk_fma_f32 v[68:69], v[110:111], v[72:73], v[38:39]
	v_pk_fma_f32 v[36:37], v[16:17], v[44:45], v[36:37]
	v_pk_mul_f32 v[228:229], v[68:69], v[246:247] op_sel_hi:[1,0]
	v_lshlrev_b32_e32 v54, 16, v137
	v_and_b32_e32 v55, 0xffff0000, v137
	v_exp_f32_e32 v228, v228
	v_pk_fma_f32 v[36:37], v[104:105], v[56:57], v[36:37]
	v_exp_f32_e32 v229, v229
	v_pk_mul_f32 v[38:39], v[40:41], v[226:227]
	v_pk_fma_f32 v[52:53], v[112:113], v[54:55], v[36:37]
	v_pk_mul_f32 v[226:227], v[52:53], v[246:247] op_sel_hi:[1,0]
	v_exp_f32_e32 v226, v226
	v_exp_f32_e32 v227, v227
	v_pk_add_f32 v[228:229], v[228:229], 1.0 op_sel_hi:[1,0]
	v_rcp_f32_e32 v228, v228
	v_rcp_f32_e32 v229, v229
	v_pk_add_f32 v[226:227], v[226:227], 1.0 op_sel_hi:[1,0]
	v_rcp_f32_e32 v226, v226
	v_pk_mul_f32 v[64:65], v[42:43], v[42:43]
	v_rcp_f32_e32 v227, v227
	v_pk_mul_f32 v[74:75], v[38:39], v[38:39]
	v_add_f32_e32 v64, v64, v65
	v_pk_mul_f32 v[36:37], v[68:69], v[228:229]
	v_add_f32_e32 v64, v74, v64
	v_pk_mul_f32 v[40:41], v[36:37], v[36:37]
	v_add_f32_e32 v64, v75, v64
	v_pk_mul_f32 v[52:53], v[52:53], v[226:227]
	v_add_f32_e32 v40, v40, v64
	v_pk_mul_f32 v[68:69], v[52:53], v[52:53]
	v_add_f32_e32 v40, v41, v40
	v_add_f32_e32 v40, v68, v40
	v_add_f32_e32 v40, v69, v40
	v_mov_b32_e32 v64, 1.0
	s_nop 1
	v_add_f32_dpp v40, v40, v40 quad_perm:[1,0,3,2] row_mask:0xf bank_mask:0xf
	s_nop 1
	v_add_f32_dpp v40, v40, v40 quad_perm:[2,3,0,1] row_mask:0xf bank_mask:0xf
	s_nop 1
	v_add_f32_dpp v40, v40, v40 row_half_mirror row_mask:0xf bank_mask:0xf
	s_nop 1
	v_add_f32_dpp v40, v40, v40 row_mirror row_mask:0xf bank_mask:0xf
	s_and_saveexec_b64 s[8:9], s[4:5]
	s_cbranch_execz .LBB0_510
	v_add_f32_e32 v40, 0x358637bd, v40
	v_mul_f32_e32 v41, 0x4b800000, v40
	v_cmp_gt_f32_e32 vcc, s48, v40
	s_nop 1
	v_cndmask_b32_e32 v40, v40, v41, vcc
	v_rsq_f32_e32 v40, v40
	s_nop 0
	v_mul_f32_e32 v41, 0x45800000, v40
	v_cndmask_b32_e32 v40, v40, v41, vcc
	v_mul_f32_e32 v64, v161, v40

.LBB0_512:
	s_or_b64 exec, exec, s[8:9]
	v_pk_fma_f32 v[50:51], v[6:7], v[50:51], 0 op_sel_hi:[1,1,0]
	v_lshlrev_b32_e32 v78, 16, v138
	v_pk_fma_f32 v[50:51], v[10:11], v[60:61], v[50:51]
	v_and_b32_e32 v79, 0xffff0000, v138
	v_pk_fma_f32 v[50:51], v[98:99], v[80:81], v[50:51]
	v_pk_fma_f32 v[46:47], v[8:9], v[46:47], 0 op_sel_hi:[1,1,0]
	v_pk_fma_f32 v[50:51], v[106:107], v[78:79], v[50:51]
	v_pk_fma_f32 v[46:47], v[12:13], v[58:59], v[46:47]
	v_pk_mul_f32 v[226:227], v[50:51], v[246:247] op_sel_hi:[1,0]
	v_exp_f32_e32 v226, v226
	v_exp_f32_e32 v227, v227
	v_lshlrev_b32_e32 v64, 16, v139
	v_pk_add_f32 v[226:227], v[226:227], 1.0 op_sel_hi:[1,0]
	v_rcp_f32_e32 v226, v226
	v_rcp_f32_e32 v227, v227
	v_and_b32_e32 v65, 0xffff0000, v139
	v_pk_fma_f32 v[46:47], v[100:101], v[66:67], v[46:47]
	v_pk_fma_f32 v[48:49], v[2:3], v[48:49], 0 op_sel_hi:[1,1,0]
	v_pk_fma_f32 v[46:47], v[108:109], v[64:65], v[46:47]
	v_pk_mul_f32 v[50:51], v[50:51], v[226:227]
	v_pk_mul_f32 v[226:227], v[46:47], v[246:247] op_sel_hi:[1,0]
	v_exp_f32_e32 v226, v226
	v_exp_f32_e32 v227, v227
	v_pk_fma_f32 v[48:49], v[14:15], v[62:63], v[48:49]
	v_lshlrev_b32_e32 v70, 16, v140
	v_and_b32_e32 v71, 0xffff0000, v140
	v_pk_fma_f32 v[48:49], v[102:103], v[72:73], v[48:49]
	v_pk_fma_f32 v[48:49], v[110:111], v[70:71], v[48:49]
	v_pk_add_f32 v[226:227], v[226:227], 1.0 op_sel_hi:[1,0]
	v_pk_mul_f32 v[228:229], v[48:49], v[246:247] op_sel_hi:[1,0]
	v_rcp_f32_e32 v226, v226
	v_rcp_f32_e32 v227, v227
	v_exp_f32_e32 v228, v228
	v_exp_f32_e32 v229, v229
	v_pk_fma_f32 v[44:45], v[4:5], v[44:45], 0 op_sel_hi:[1,1,0]
	v_lshlrev_b32_e32 v52, 16, v141
	v_pk_fma_f32 v[44:45], v[16:17], v[56:57], v[44:45]
	v_and_b32_e32 v53, 0xffff0000, v141
	v_pk_fma_f32 v[44:45], v[104:105], v[54:55], v[44:45]
	v_pk_mul_f32 v[46:47], v[46:47], v[226:227]
	v_pk_add_f32 v[228:229], v[228:229], 1.0 op_sel_hi:[1,0]
	v_pk_fma_f32 v[76:77], v[112:113], v[52:53], v[44:45]
	v_rcp_f32_e32 v228, v228
	v_pk_mul_f32 v[226:227], v[76:77], v[246:247] op_sel_hi:[1,0]
	v_exp_f32_e32 v226, v226
	v_exp_f32_e32 v227, v227
	v_rcp_f32_e32 v229, v229
	v_pk_add_f32 v[226:227], v[226:227], 1.0 op_sel_hi:[1,0]
	v_rcp_f32_e32 v226, v226
	v_pk_mul_f32 v[74:75], v[50:51], v[50:51]
	v_rcp_f32_e32 v227, v227
	v_pk_mul_f32 v[84:85], v[46:47], v[46:47]
	v_add_f32_e32 v74, v74, v75
	v_pk_mul_f32 v[44:45], v[48:49], v[228:229]
	v_add_f32_e32 v74, v84, v74
	v_pk_mul_f32 v[48:49], v[44:45], v[44:45]
	v_add_f32_e32 v74, v85, v74
	v_pk_mul_f32 v[68:69], v[76:77], v[226:227]
	v_add_f32_e32 v48, v48, v74
	v_pk_mul_f32 v[76:77], v[68:69], v[68:69]
	v_add_f32_e32 v48, v49, v48
	v_add_f32_e32 v48, v76, v48
	v_add_f32_e32 v48, v77, v48
	v_mov_b32_e32 v74, 1.0
	s_nop 1
	v_add_f32_dpp v48, v48, v48 quad_perm:[1,0,3,2] row_mask:0xf bank_mask:0xf
	s_nop 1
	v_add_f32_dpp v48, v48, v48 quad_perm:[2,3,0,1] row_mask:0xf bank_mask:0xf
	s_nop 1
	v_add_f32_dpp v48, v48, v48 row_half_mirror row_mask:0xf bank_mask:0xf
	s_nop 1
	v_add_f32_dpp v48, v48, v48 row_mirror row_mask:0xf bank_mask:0xf
	s_and_saveexec_b64 s[8:9], s[4:5]
	s_cbranch_execz .LBB0_514
	v_add_f32_e32 v48, 0x358637bd, v48
	v_mul_f32_e32 v49, 0x4b800000, v48
	v_cmp_gt_f32_e32 vcc, s48, v48
	s_nop 1
	v_cndmask_b32_e32 v48, v48, v49, vcc
	v_rsq_f32_e32 v48, v48
	s_nop 0
	v_mul_f32_e32 v49, 0x45800000, v48
	v_cndmask_b32_e32 v48, v48, v49, vcc
	v_mul_f32_e32 v74, v161, v48

.LBB0_516:
	s_or_b64 exec, exec, s[8:9]
	v_pk_fma_f32 v[60:61], v[6:7], v[60:61], 0 op_sel_hi:[1,1,0]
	v_lshlrev_b32_e32 v82, 16, v142
	v_pk_fma_f32 v[60:61], v[10:11], v[80:81], v[60:61]
	v_and_b32_e32 v83, 0xffff0000, v142
	v_pk_fma_f32 v[60:61], v[98:99], v[78:79], v[60:61]
	v_pk_fma_f32 v[58:59], v[8:9], v[58:59], 0 op_sel_hi:[1,1,0]
	v_pk_fma_f32 v[68:69], v[106:107], v[82:83], v[60:61]
	v_pk_fma_f32 v[58:59], v[12:13], v[66:67], v[58:59]
	v_pk_mul_f32 v[226:227], v[68:69], v[246:247] op_sel_hi:[1,0]
	v_exp_f32_e32 v226, v226
	v_exp_f32_e32 v227, v227
	v_lshlrev_b32_e32 v76, 16, v143
	v_pk_add_f32 v[226:227], v[226:227], 1.0 op_sel_hi:[1,0]
	v_rcp_f32_e32 v226, v226
	v_rcp_f32_e32 v227, v227
	v_and_b32_e32 v77, 0xffff0000, v143
	v_pk_fma_f32 v[58:59], v[100:101], v[64:65], v[58:59]
	v_pk_fma_f32 v[62:63], v[2:3], v[62:63], 0 op_sel_hi:[1,1,0]
	v_pk_fma_f32 v[58:59], v[108:109], v[76:77], v[58:59]
	v_pk_mul_f32 v[68:69], v[68:69], v[226:227]
	v_pk_mul_f32 v[226:227], v[58:59], v[246:247] op_sel_hi:[1,0]
	v_exp_f32_e32 v226, v226
	v_exp_f32_e32 v227, v227
	v_pk_fma_f32 v[62:63], v[14:15], v[72:73], v[62:63]
	v_lshlrev_b32_e32 v74, 16, v144
	v_and_b32_e32 v75, 0xffff0000, v144
	v_pk_fma_f32 v[62:63], v[102:103], v[70:71], v[62:63]
	v_pk_fma_f32 v[62:63], v[110:111], v[74:75], v[62:63]
	v_pk_add_f32 v[226:227], v[226:227], 1.0 op_sel_hi:[1,0]
	v_pk_mul_f32 v[228:229], v[62:63], v[246:247] op_sel_hi:[1,0]
	v_rcp_f32_e32 v226, v226
	v_rcp_f32_e32 v227, v227
	v_exp_f32_e32 v228, v228
	v_exp_f32_e32 v229, v229
	v_pk_fma_f32 v[56:57], v[4:5], v[56:57], 0 op_sel_hi:[1,1,0]
	v_lshlrev_b32_e32 v60, 16, v145
	v_pk_fma_f32 v[56:57], v[16:17], v[54:55], v[56:57]
	v_and_b32_e32 v61, 0xffff0000, v145
	v_pk_fma_f32 v[56:57], v[104:105], v[52:53], v[56:57]
	v_pk_mul_f32 v[58:59], v[58:59], v[226:227]
	v_pk_add_f32 v[228:229], v[228:229], 1.0 op_sel_hi:[1,0]
	v_pk_fma_f32 v[88:89], v[112:113], v[60:61], v[56:57]
	v_rcp_f32_e32 v228, v228
	v_pk_mul_f32 v[226:227], v[88:89], v[246:247] op_sel_hi:[1,0]
	v_exp_f32_e32 v226, v226
	v_exp_f32_e32 v227, v227
	v_rcp_f32_e32 v229, v229
	v_pk_add_f32 v[226:227], v[226:227], 1.0 op_sel_hi:[1,0]
	v_rcp_f32_e32 v226, v226
	v_pk_mul_f32 v[86:87], v[68:69], v[68:69]
	v_rcp_f32_e32 v227, v227
	v_pk_mul_f32 v[92:93], v[58:59], v[58:59]
	v_add_f32_e32 v86, v86, v87
	v_pk_mul_f32 v[56:57], v[62:63], v[228:229]
	v_add_f32_e32 v86, v92, v86
	v_pk_mul_f32 v[62:63], v[56:57], v[56:57]
	v_add_f32_e32 v86, v93, v86
	v_pk_mul_f32 v[84:85], v[88:89], v[226:227]
	v_add_f32_e32 v62, v62, v86
	v_pk_mul_f32 v[88:89], v[84:85], v[84:85]
	v_add_f32_e32 v62, v63, v62
	v_add_f32_e32 v62, v88, v62
	v_add_f32_e32 v62, v89, v62
	v_mov_b32_e32 v86, 1.0
	s_nop 1
	v_add_f32_dpp v62, v62, v62 quad_perm:[1,0,3,2] row_mask:0xf bank_mask:0xf
	s_nop 1
	v_add_f32_dpp v62, v62, v62 quad_perm:[2,3,0,1] row_mask:0xf bank_mask:0xf
	s_nop 1
	v_add_f32_dpp v62, v62, v62 row_half_mirror row_mask:0xf bank_mask:0xf
	s_nop 1
	v_add_f32_dpp v62, v62, v62 row_mirror row_mask:0xf bank_mask:0xf
	s_and_saveexec_b64 s[8:9], s[4:5]
	s_cbranch_execz .LBB0_518
	v_add_f32_e32 v62, 0x358637bd, v62
	v_mul_f32_e32 v63, 0x4b800000, v62
	v_cmp_gt_f32_e32 vcc, s48, v62
	s_nop 1
	v_cndmask_b32_e32 v62, v62, v63, vcc
	v_rsq_f32_e32 v62, v62
	s_nop 0
	v_mul_f32_e32 v63, 0x45800000, v62
	v_cndmask_b32_e32 v62, v62, v63, vcc
	v_mul_f32_e32 v86, v161, v62

.LBB0_520:
	s_or_b64 exec, exec, s[8:9]
	v_pk_fma_f32 v[80:81], v[6:7], v[80:81], 0 op_sel_hi:[1,1,0]
	v_lshlrev_b32_e32 v90, 16, v146
	v_pk_fma_f32 v[80:81], v[10:11], v[78:79], v[80:81]
	v_and_b32_e32 v91, 0xffff0000, v146
	v_pk_fma_f32 v[80:81], v[98:99], v[82:83], v[80:81]
	v_pk_fma_f32 v[66:67], v[8:9], v[66:67], 0 op_sel_hi:[1,1,0]
	v_pk_fma_f32 v[84:85], v[106:107], v[90:91], v[80:81]
	v_pk_fma_f32 v[66:67], v[12:13], v[64:65], v[66:67]
	v_pk_mul_f32 v[226:227], v[84:85], v[246:247] op_sel_hi:[1,0]
	v_exp_f32_e32 v226, v226
	v_exp_f32_e32 v227, v227
	v_lshlrev_b32_e32 v88, 16, v147
	v_pk_add_f32 v[226:227], v[226:227], 1.0 op_sel_hi:[1,0]
	v_rcp_f32_e32 v226, v226
	v_rcp_f32_e32 v227, v227
	v_and_b32_e32 v89, 0xffff0000, v147
	v_pk_fma_f32 v[66:67], v[100:101], v[76:77], v[66:67]
	v_pk_fma_f32 v[72:73], v[2:3], v[72:73], 0 op_sel_hi:[1,1,0]
	v_pk_fma_f32 v[66:67], v[108:109], v[88:89], v[66:67]
	v_pk_mul_f32 v[84:85], v[84:85], v[226:227]
	v_pk_mul_f32 v[226:227], v[66:67], v[246:247] op_sel_hi:[1,0]
	v_exp_f32_e32 v226, v226
	v_exp_f32_e32 v227, v227
	v_pk_fma_f32 v[72:73], v[14:15], v[70:71], v[72:73]
	v_lshlrev_b32_e32 v86, 16, v148
	v_and_b32_e32 v87, 0xffff0000, v148
	v_pk_fma_f32 v[72:73], v[102:103], v[74:75], v[72:73]
	v_pk_fma_f32 v[72:73], v[110:111], v[86:87], v[72:73]
	v_pk_add_f32 v[226:227], v[226:227], 1.0 op_sel_hi:[1,0]
	v_pk_mul_f32 v[228:229], v[72:73], v[246:247] op_sel_hi:[1,0]
	v_rcp_f32_e32 v226, v226
	v_rcp_f32_e32 v227, v227
	v_exp_f32_e32 v228, v228
	v_exp_f32_e32 v229, v229
	v_pk_fma_f32 v[54:55], v[4:5], v[54:55], 0 op_sel_hi:[1,1,0]
	v_lshlrev_b32_e32 v80, 16, v149
	v_pk_fma_f32 v[54:55], v[16:17], v[52:53], v[54:55]
	v_and_b32_e32 v81, 0xffff0000, v149
	v_pk_fma_f32 v[54:55], v[104:105], v[60:61], v[54:55]
	v_pk_mul_f32 v[66:67], v[66:67], v[226:227]
	v_pk_add_f32 v[228:229], v[228:229], 1.0 op_sel_hi:[1,0]
	v_pk_fma_f32 v[96:97], v[112:113], v[80:81], v[54:55]
	v_rcp_f32_e32 v228, v228
	v_pk_mul_f32 v[226:227], v[96:97], v[246:247] op_sel_hi:[1,0]
	v_exp_f32_e32 v226, v226
	v_exp_f32_e32 v227, v227
	v_rcp_f32_e32 v229, v229
	v_pk_add_f32 v[226:227], v[226:227], 1.0 op_sel_hi:[1,0]
	v_rcp_f32_e32 v226, v226
	v_pk_mul_f32 v[94:95], v[84:85], v[84:85]
	v_rcp_f32_e32 v227, v227
	v_pk_mul_f32 v[164:165], v[66:67], v[66:67]
	v_add_f32_e32 v94, v94, v95
	v_pk_mul_f32 v[54:55], v[72:73], v[228:229]
	v_add_f32_e32 v94, v164, v94
	v_pk_mul_f32 v[72:73], v[54:55], v[54:55]
	v_add_f32_e32 v94, v165, v94
	v_pk_mul_f32 v[92:93], v[96:97], v[226:227]
	v_add_f32_e32 v72, v72, v94
	v_pk_mul_f32 v[96:97], v[92:93], v[92:93]
	v_add_f32_e32 v72, v73, v72
	v_add_f32_e32 v72, v96, v72
	v_add_f32_e32 v72, v97, v72
	v_mov_b32_e32 v94, 1.0
	s_nop 1
	v_add_f32_dpp v72, v72, v72 quad_perm:[1,0,3,2] row_mask:0xf bank_mask:0xf
	s_nop 1
	v_add_f32_dpp v72, v72, v72 quad_perm:[2,3,0,1] row_mask:0xf bank_mask:0xf
	s_nop 1
	v_add_f32_dpp v72, v72, v72 row_half_mirror row_mask:0xf bank_mask:0xf
	s_nop 1
	v_add_f32_dpp v72, v72, v72 row_mirror row_mask:0xf bank_mask:0xf
	s_and_saveexec_b64 s[8:9], s[4:5]
	s_cbranch_execz .LBB0_522
	v_add_f32_e32 v72, 0x358637bd, v72
	v_mul_f32_e32 v73, 0x4b800000, v72
	v_cmp_gt_f32_e32 vcc, s48, v72
	s_nop 1
	v_cndmask_b32_e32 v72, v72, v73, vcc
	v_rsq_f32_e32 v72, v72
	s_nop 0
	v_mul_f32_e32 v73, 0x45800000, v72
	v_cndmask_b32_e32 v72, v72, v73, vcc
	v_mul_f32_e32 v94, v161, v72

.LBB0_524:
	s_or_b64 exec, exec, s[8:9]
	v_pk_fma_f32 v[78:79], v[6:7], v[78:79], 0 op_sel_hi:[1,1,0]
	v_lshlrev_b32_e32 v162, 16, v150
	v_pk_fma_f32 v[78:79], v[10:11], v[82:83], v[78:79]
	v_and_b32_e32 v163, 0xffff0000, v150
	v_pk_fma_f32 v[78:79], v[98:99], v[90:91], v[78:79]
	v_pk_fma_f32 v[64:65], v[8:9], v[64:65], 0 op_sel_hi:[1,1,0]
	v_pk_fma_f32 v[78:79], v[106:107], v[162:163], v[78:79]
	v_pk_fma_f32 v[64:65], v[12:13], v[76:77], v[64:65]
	v_pk_mul_f32 v[226:227], v[78:79], v[246:247] op_sel_hi:[1,0]
	v_exp_f32_e32 v226, v226
	v_exp_f32_e32 v227, v227
	v_lshlrev_b32_e32 v96, 16, v151
	v_pk_add_f32 v[226:227], v[226:227], 1.0 op_sel_hi:[1,0]
	v_rcp_f32_e32 v226, v226
	v_rcp_f32_e32 v227, v227
	v_and_b32_e32 v97, 0xffff0000, v151
	v_pk_fma_f32 v[64:65], v[100:101], v[88:89], v[64:65]
	v_pk_fma_f32 v[70:71], v[2:3], v[70:71], 0 op_sel_hi:[1,1,0]
	v_pk_fma_f32 v[64:65], v[108:109], v[96:97], v[64:65]
	v_pk_mul_f32 v[78:79], v[78:79], v[226:227]
	v_pk_mul_f32 v[226:227], v[64:65], v[246:247] op_sel_hi:[1,0]
	v_exp_f32_e32 v226, v226
	v_exp_f32_e32 v227, v227
	v_pk_fma_f32 v[70:71], v[14:15], v[74:75], v[70:71]
	v_lshlrev_b32_e32 v94, 16, v152
	v_and_b32_e32 v95, 0xffff0000, v152
	v_pk_fma_f32 v[70:71], v[102:103], v[86:87], v[70:71]
	v_pk_fma_f32 v[70:71], v[110:111], v[94:95], v[70:71]
	v_pk_add_f32 v[226:227], v[226:227], 1.0 op_sel_hi:[1,0]
	v_pk_mul_f32 v[228:229], v[70:71], v[246:247] op_sel_hi:[1,0]
	v_rcp_f32_e32 v226, v226
	v_rcp_f32_e32 v227, v227
	v_exp_f32_e32 v228, v228
	v_pk_fma_f32 v[52:53], v[4:5], v[52:53], 0 op_sel_hi:[1,1,0]
	v_exp_f32_e32 v229, v229
	v_pk_fma_f32 v[52:53], v[16:17], v[60:61], v[52:53]
	v_lshlrev_b32_e32 v92, 16, v153
	v_and_b32_e32 v93, 0xffff0000, v153
	v_pk_fma_f32 v[52:53], v[104:105], v[80:81], v[52:53]
	v_pk_mul_f32 v[64:65], v[64:65], v[226:227]
	v_pk_fma_f32 v[52:53], v[112:113], v[92:93], v[52:53]
	v_pk_mul_f32 v[226:227], v[52:53], v[246:247] op_sel_hi:[1,0]
	v_pk_add_f32 v[228:229], v[228:229], 1.0 op_sel_hi:[1,0]
	v_exp_f32_e32 v226, v226
	v_exp_f32_e32 v227, v227
	v_rcp_f32_e32 v228, v228
	v_rcp_f32_e32 v229, v229
	v_pk_add_f32 v[226:227], v[226:227], 1.0 op_sel_hi:[1,0]
	v_rcp_f32_e32 v226, v226
	v_pk_mul_f32 v[176:177], v[78:79], v[78:79]
	v_rcp_f32_e32 v227, v227
	v_pk_mul_f32 v[180:181], v[64:65], v[64:65]
	v_add_f32_e32 v166, v176, v177
	v_pk_mul_f32 v[70:71], v[70:71], v[228:229]
	v_add_f32_e32 v166, v180, v166
	v_pk_mul_f32 v[182:183], v[70:71], v[70:71]
	v_add_f32_e32 v166, v181, v166
	v_pk_mul_f32 v[164:165], v[52:53], v[226:227]
	v_add_f32_e32 v166, v182, v166
	v_pk_mul_f32 v[52:53], v[164:165], v[164:165]
	v_add_f32_e32 v166, v183, v166
	v_add_f32_e32 v52, v52, v166
	v_add_f32_e32 v52, v53, v52
	v_mov_b32_e32 v166, 1.0
	s_nop 1
	v_add_f32_dpp v52, v52, v52 quad_perm:[1,0,3,2] row_mask:0xf bank_mask:0xf
	s_nop 1
	v_add_f32_dpp v52, v52, v52 quad_perm:[2,3,0,1] row_mask:0xf bank_mask:0xf
	s_nop 1
	v_add_f32_dpp v52, v52, v52 row_half_mirror row_mask:0xf bank_mask:0xf
	s_nop 1
	v_add_f32_dpp v52, v52, v52 row_mirror row_mask:0xf bank_mask:0xf
	s_and_saveexec_b64 s[8:9], s[4:5]
	s_cbranch_execz .LBB0_526
	v_add_f32_e32 v52, 0x358637bd, v52
	v_mul_f32_e32 v53, 0x4b800000, v52
	v_cmp_gt_f32_e32 vcc, s48, v52
	s_nop 1
	v_cndmask_b32_e32 v52, v52, v53, vcc
	v_rsq_f32_e32 v52, v52
	s_nop 0
	v_mul_f32_e32 v53, 0x45800000, v52
	v_cndmask_b32_e32 v52, v52, v53, vcc
	v_mul_f32_e32 v166, v161, v52

.LBB0_528:
	s_or_b64 exec, exec, s[8:9]
	v_pk_fma_f32 v[82:83], v[6:7], v[82:83], 0 op_sel_hi:[1,1,0]
	v_pk_fma_f32 v[76:77], v[8:9], v[76:77], 0 op_sel_hi:[1,1,0]
	v_pk_fma_f32 v[82:83], v[10:11], v[90:91], v[82:83]
	v_lshlrev_b32_e32 v90, 16, v154
	v_pk_fma_f32 v[82:83], v[98:99], v[162:163], v[82:83]
	v_and_b32_e32 v91, 0xffff0000, v154
	v_pk_fma_f32 v[82:83], v[106:107], v[90:91], v[82:83]
	v_pk_fma_f32 v[76:77], v[12:13], v[88:89], v[76:77]
	v_pk_mul_f32 v[226:227], v[82:83], v[246:247] op_sel_hi:[1,0]
	v_exp_f32_e32 v226, v226
	v_exp_f32_e32 v227, v227
	v_pk_fma_f32 v[76:77], v[100:101], v[96:97], v[76:77]
	v_lshlrev_b32_e32 v88, 16, v155
	v_pk_add_f32 v[226:227], v[226:227], 1.0 op_sel_hi:[1,0]
	v_rcp_f32_e32 v226, v226
	v_rcp_f32_e32 v227, v227
	v_and_b32_e32 v89, 0xffff0000, v155
	v_pk_fma_f32 v[76:77], v[108:109], v[88:89], v[76:77]
	v_pk_fma_f32 v[74:75], v[2:3], v[74:75], 0 op_sel_hi:[1,1,0]
	v_pk_mul_f32 v[228:229], v[76:77], v[246:247] op_sel_hi:[1,0]
	v_pk_mul_f32 v[82:83], v[82:83], v[226:227]
	v_exp_f32_e32 v228, v228
	v_exp_f32_e32 v229, v229
	v_pk_fma_f32 v[74:75], v[14:15], v[86:87], v[74:75]
	v_lshlrev_b32_e32 v86, 16, v156
	v_pk_fma_f32 v[74:75], v[102:103], v[94:95], v[74:75]
	v_and_b32_e32 v87, 0xffff0000, v156
	v_pk_fma_f32 v[86:87], v[110:111], v[86:87], v[74:75]
	v_pk_fma_f32 v[60:61], v[4:5], v[60:61], 0 op_sel_hi:[1,1,0]
	v_pk_mul_f32 v[226:227], v[86:87], v[246:247] op_sel_hi:[1,0]
	v_pk_fma_f32 v[60:61], v[16:17], v[80:81], v[60:61]
	v_pk_add_f32 v[228:229], v[228:229], 1.0 op_sel_hi:[1,0]
	v_exp_f32_e32 v226, v226
	v_pk_fma_f32 v[60:61], v[104:105], v[92:93], v[60:61]
	v_lshlrev_b32_e32 v80, 16, v157
	v_and_b32_e32 v81, 0xffff0000, v157
	v_rcp_f32_e32 v228, v228
	v_rcp_f32_e32 v229, v229
	v_exp_f32_e32 v227, v227
	v_pk_fma_f32 v[60:61], v[112:113], v[80:81], v[60:61]
	v_pk_mul_f32 v[88:89], v[82:83], v[82:83]
	v_pk_mul_f32 v[230:231], v[60:61], v[246:247] op_sel_hi:[1,0]
	v_exp_f32_e32 v230, v230
	v_exp_f32_e32 v231, v231
	v_pk_mul_f32 v[74:75], v[76:77], v[228:229]
	v_pk_add_f32 v[226:227], v[226:227], 1.0 op_sel_hi:[1,0]
	v_rcp_f32_e32 v226, v226
	v_rcp_f32_e32 v227, v227
	v_pk_add_f32 v[230:231], v[230:231], 1.0 op_sel_hi:[1,0]
	v_rcp_f32_e32 v230, v230
	v_rcp_f32_e32 v231, v231
	v_pk_mul_f32 v[90:91], v[74:75], v[74:75]
	v_add_f32_e32 v88, v88, v89
	v_pk_mul_f32 v[76:77], v[86:87], v[226:227]
	v_add_f32_e32 v88, v90, v88
	v_pk_mul_f32 v[86:87], v[76:77], v[76:77]
	v_add_f32_e32 v88, v91, v88
	v_pk_mul_f32 v[80:81], v[60:61], v[230:231]
	v_add_f32_e32 v86, v86, v88
	v_pk_mul_f32 v[60:61], v[80:81], v[80:81]
	v_add_f32_e32 v86, v87, v86
	v_add_f32_e32 v60, v60, v86
	v_add_f32_e32 v60, v61, v60
	v_mov_b32_e32 v86, 1.0
	s_nop 1
	v_add_f32_dpp v19, v60, v60 quad_perm:[1,0,3,2] row_mask:0xf bank_mask:0xf
	s_nop 1
	v_add_f32_dpp v19, v19, v19 quad_perm:[2,3,0,1] row_mask:0xf bank_mask:0xf
	s_nop 1
	v_add_f32_dpp v19, v19, v19 row_half_mirror row_mask:0xf bank_mask:0xf
	s_nop 1
	v_add_f32_dpp v19, v19, v19 row_mirror row_mask:0xf bank_mask:0xf
	s_and_saveexec_b64 s[8:9], s[4:5]
	s_cbranch_execz .LBB0_530
	v_add_f32_e32 v19, 0x358637bd, v19
	v_mul_f32_e32 v60, 0x4b800000, v19
	v_cmp_gt_f32_e32 vcc, s48, v19
	s_nop 1
	v_cndmask_b32_e32 v19, v19, v60, vcc
	v_rsq_f32_e32 v19, v19
	s_nop 0
	v_mul_f32_e32 v60, 0x45800000, v19
	v_cndmask_b32_e32 v19, v19, v60, vcc
	v_mul_f32_e32 v86, v161, v19
